# FINAL residual/RMSNorm pass fused into P13's epilogue (hand-written two-stage epilogue with a per-unit team barrier); separate FINAL phase and its seam removed
# speedup vs baseline: 1.0126x; 1.0126x over previous
; __device__ __forceinline__ float bf_lo(unsigned w) { return __uint_as_float(w << 16); }
; __device__ __forceinline__ float bf_hi(unsigned w) { return __uint_as_float(w & 0xffff0000u); }
; __device__ __forceinline__ float sigmoid_fast(float x) { return __builtin_amdgcn_rcpf(1.0f + __builtin_amdgcn_exp2f(-1.44269504089f * x)); }
;     __device__ __forceinline__ void operator()(const pg8::f32x4 (&acc)[2][2][4][2], const pg8::Unit& u, int wr, int wc, int fr, int fq) const {
;     ...
;             if (GATE) {
; #pragma unroll
;                 for (int m = 0; m < 4; ++m)
; #pragma unroll
;                     for (int bj = 0; bj < 2; ++bj) gq[m][bj] = *(const v4u*)(G + (size_t)(row0 + ai * 128 + m * 16) * D + col0 + bj * 128);
;             }
;             if (ADD) {
; #pragma unroll
;                 for (int m = 0; m < 4; ++m)
; #pragma unroll
;                     for (int bj = 0; bj < 2; ++bj) aq[m][bj] = *(const v4u*)(A2 + (size_t)(row0 + ai * 128 + m * 16) * D + col0 + bj * 128);
;             }
; #pragma unroll
;             for (int m = 0; m < 4; ++m) {
;                 const int row = row0 + ai * 128 + m * 16;
;                 const size_t off = (size_t)row * D + col0;
;                 float s = 0.f;
; #pragma unroll
;                 for (int bj = 0; bj < 2; ++bj) {
;                     float r[8];
; #pragma unroll
;                     for (int j = 0; j < 4; ++j) { r[j] = acc[ai][bj][m][0][j]; r[4 + j] = acc[ai][bj][m][1][j]; }
;                     if (RSCALE) { const float rv = rvs[ai][m];
; #pragma unroll
;                         for (int j = 0; j < 8; ++j) r[j] *= rv; }
;                     if (ACT == 1) {
; #pragma unroll
;                         for (int j = 0; j < 8; ++j) r[j] = sigmoid_fast(r[j]);
;                     }
;                     if (GATE) { const v4u g = gq[m][bj];
;                         r[0] *= bf_lo(g.x); r[1] *= bf_hi(g.x); r[2] *= bf_lo(g.y); r[3] *= bf_hi(g.y); r[4] *= bf_lo(g.z); r[5] *= bf_hi(g.z); r[6] *= bf_lo(g.w); r[7] *= bf_hi(g.w); }
;                     if (ADD) { const v4u g = aq[m][bj];
;                         r[0] += bf_lo(g.x); r[1] += bf_hi(g.x); r[2] += bf_lo(g.y); r[3] += bf_hi(g.y); r[4] += bf_lo(g.z); r[5] += bf_hi(g.z); r[6] += bf_lo(g.w); r[7] += bf_hi(g.w); }
;                     if (PART) {
; #pragma unroll
;                         for (int j = 0; j < 8; ++j) s += r[j] * r[j];
.LBB0_1392:
	s_waitcnt lgkmcnt(0)
	v_lshl_or_b32 v128, s58, 8, v172
	v_lshl_add_u32 v154, s57, 8, v170
	v_lshlrev_b32_e32 v156, 2, v128
	v_lshlrev_b32_e32 v129, 1, v128
	v_lshl_add_u32 v152, v154, 11, v129
	v_xor_b32_e32 v130, 16, v176
	v_lshlrev_b32_e32 v177, 2, v130
	v_xor_b32_e32 v130, 32, v176
	v_lshlrev_b32_e32 v155, 2, v130
	v_lshrrev_b32_e32 v130, 4, v176
	v_and_b32_e32 v130, 3, v130
	v_lshlrev_b32_e32 v157, 4, v130
	s_lshl_b32 s38, s58, 4
	s_add_u32 s38, s38, s14
	v_lshl_add_u32 v153, v154, 6, s38
	global_load_dwordx4 v[178:181], v152, s[16:17]
	global_load_dwordx4 v[182:185], v152, s[16:17] offset:256
	v_add_u32_e32 v159, 0x8000, v152
	global_load_dwordx4 v[186:189], v159, s[16:17]
	global_load_dwordx4 v[190:193], v159, s[16:17] offset:256
	v_add_u32_e32 v160, 0x10000, v152
	global_load_dwordx4 v[196:199], v160, s[16:17]
	global_load_dwordx4 v[200:203], v160, s[16:17] offset:256
	v_add_u32_e32 v161, 0x18000, v152
	global_load_dwordx4 v[204:207], v161, s[16:17]
	global_load_dwordx4 v[208:211], v161, s[16:17] offset:256
	v_add_u32_e32 v162, 0x40000, v152
	global_load_dwordx4 v[212:215], v162, s[16:17]
	global_load_dwordx4 v[216:219], v162, s[16:17] offset:256
	v_add_u32_e32 v163, 0x48000, v152
	global_load_dwordx4 v[220:223], v163, s[16:17]
	global_load_dwordx4 v[224:227], v163, s[16:17] offset:256
	v_add_u32_e32 v164, 0x50000, v152
	global_load_dwordx4 v[228:231], v164, s[16:17]
	global_load_dwordx4 v[232:235], v164, s[16:17] offset:256
	v_add_u32_e32 v165, 0x58000, v152
	global_load_dwordx4 v[236:239], v165, s[16:17]
	global_load_dwordx4 v[240:243], v165, s[16:17] offset:256
	s_waitcnt vmcnt(14)
	v_lshlrev_b32_e32 v248, 16, v178
	v_and_b32_e32 v249, 0xffff0000, v178
	v_pk_mul_f32 v[124:125], v[124:125], v[248:249]
	v_lshlrev_b32_e32 v250, 16, v179
	v_and_b32_e32 v251, 0xffff0000, v179
	v_pk_mul_f32 v[126:127], v[126:127], v[250:251]
	v_lshlrev_b32_e32 v252, 16, v180
	v_and_b32_e32 v253, 0xffff0000, v180
	v_pk_mul_f32 v[120:121], v[120:121], v[252:253]
	v_lshlrev_b32_e32 v248, 16, v181
	v_and_b32_e32 v249, 0xffff0000, v181
	v_pk_mul_f32 v[122:123], v[122:123], v[248:249]
	v_lshlrev_b32_e32 v250, 16, v182
	v_and_b32_e32 v251, 0xffff0000, v182
	v_pk_mul_f32 v[116:117], v[116:117], v[250:251]
	v_lshlrev_b32_e32 v252, 16, v183
	v_and_b32_e32 v253, 0xffff0000, v183
	v_pk_mul_f32 v[118:119], v[118:119], v[252:253]
	v_lshlrev_b32_e32 v248, 16, v184
	v_and_b32_e32 v249, 0xffff0000, v184
	v_pk_mul_f32 v[112:113], v[112:113], v[248:249]
	v_lshlrev_b32_e32 v250, 16, v185
	v_and_b32_e32 v251, 0xffff0000, v185
	v_pk_mul_f32 v[114:115], v[114:115], v[250:251]
	v_pk_mul_f32 v[244:245], v[124:125], v[124:125]
	v_pk_fma_f32 v[244:245], v[126:127], v[126:127], v[244:245]
	v_pk_fma_f32 v[244:245], v[120:121], v[120:121], v[244:245]
	v_pk_fma_f32 v[244:245], v[122:123], v[122:123], v[244:245]
	v_pk_fma_f32 v[244:245], v[116:117], v[116:117], v[244:245]
	v_pk_fma_f32 v[244:245], v[118:119], v[118:119], v[244:245]
	v_pk_fma_f32 v[244:245], v[112:113], v[112:113], v[244:245]
	v_pk_fma_f32 v[244:245], v[114:115], v[114:115], v[244:245]
	v_add_f32_e32 v128, v244, v245
	s_waitcnt vmcnt(12)
	v_lshlrev_b32_e32 v248, 16, v186
	v_and_b32_e32 v249, 0xffff0000, v186
	v_pk_mul_f32 v[108:109], v[108:109], v[248:249]
	v_lshlrev_b32_e32 v250, 16, v187
	v_and_b32_e32 v251, 0xffff0000, v187
	v_pk_mul_f32 v[110:111], v[110:111], v[250:251]
	v_lshlrev_b32_e32 v252, 16, v188
	v_and_b32_e32 v253, 0xffff0000, v188
	v_pk_mul_f32 v[104:105], v[104:105], v[252:253]
	v_lshlrev_b32_e32 v248, 16, v189
	v_and_b32_e32 v249, 0xffff0000, v189
	v_pk_mul_f32 v[106:107], v[106:107], v[248:249]
	v_lshlrev_b32_e32 v250, 16, v190
	v_and_b32_e32 v251, 0xffff0000, v190
	v_pk_mul_f32 v[100:101], v[100:101], v[250:251]
	v_lshlrev_b32_e32 v252, 16, v191
	v_and_b32_e32 v253, 0xffff0000, v191
	v_pk_mul_f32 v[102:103], v[102:103], v[252:253]
	v_lshlrev_b32_e32 v248, 16, v192
	v_and_b32_e32 v249, 0xffff0000, v192
	v_pk_mul_f32 v[96:97], v[96:97], v[248:249]
	v_lshlrev_b32_e32 v250, 16, v193
	v_and_b32_e32 v251, 0xffff0000, v193
	v_pk_mul_f32 v[98:99], v[98:99], v[250:251]
	v_pk_mul_f32 v[244:245], v[108:109], v[108:109]
	v_pk_fma_f32 v[244:245], v[110:111], v[110:111], v[244:245]
	v_pk_fma_f32 v[244:245], v[104:105], v[104:105], v[244:245]
	v_pk_fma_f32 v[244:245], v[106:107], v[106:107], v[244:245]
	v_pk_fma_f32 v[244:245], v[100:101], v[100:101], v[244:245]
	v_pk_fma_f32 v[244:245], v[102:103], v[102:103], v[244:245]
	v_pk_fma_f32 v[244:245], v[96:97], v[96:97], v[244:245]
	v_pk_fma_f32 v[244:245], v[98:99], v[98:99], v[244:245]
	v_add_f32_e32 v129, v244, v245
	s_waitcnt vmcnt(10)
	v_lshlrev_b32_e32 v248, 16, v196
	v_and_b32_e32 v249, 0xffff0000, v196
	v_pk_mul_f32 v[92:93], v[92:93], v[248:249]
	v_lshlrev_b32_e32 v250, 16, v197
	v_and_b32_e32 v251, 0xffff0000, v197
	v_pk_mul_f32 v[94:95], v[94:95], v[250:251]
	v_lshlrev_b32_e32 v252, 16, v198
	v_and_b32_e32 v253, 0xffff0000, v198
	v_pk_mul_f32 v[88:89], v[88:89], v[252:253]
	v_lshlrev_b32_e32 v248, 16, v199
	v_and_b32_e32 v249, 0xffff0000, v199
	v_pk_mul_f32 v[90:91], v[90:91], v[248:249]
	v_lshlrev_b32_e32 v250, 16, v200
	v_and_b32_e32 v251, 0xffff0000, v200
	v_pk_mul_f32 v[84:85], v[84:85], v[250:251]
	v_lshlrev_b32_e32 v252, 16, v201
	v_and_b32_e32 v253, 0xffff0000, v201
	v_pk_mul_f32 v[86:87], v[86:87], v[252:253]
	v_lshlrev_b32_e32 v248, 16, v202
	v_and_b32_e32 v249, 0xffff0000, v202
	v_pk_mul_f32 v[80:81], v[80:81], v[248:249]
	v_lshlrev_b32_e32 v250, 16, v203
	v_and_b32_e32 v251, 0xffff0000, v203
	v_pk_mul_f32 v[82:83], v[82:83], v[250:251]
	v_pk_mul_f32 v[244:245], v[92:93], v[92:93]
	v_pk_fma_f32 v[244:245], v[94:95], v[94:95], v[244:245]
	v_pk_fma_f32 v[244:245], v[88:89], v[88:89], v[244:245]
	v_pk_fma_f32 v[244:245], v[90:91], v[90:91], v[244:245]
	v_pk_fma_f32 v[244:245], v[84:85], v[84:85], v[244:245]
	v_pk_fma_f32 v[244:245], v[86:87], v[86:87], v[244:245]
	v_pk_fma_f32 v[244:245], v[80:81], v[80:81], v[244:245]
	v_pk_fma_f32 v[244:245], v[82:83], v[82:83], v[244:245]
	v_add_f32_e32 v130, v244, v245
	s_waitcnt vmcnt(8)
; __device__ __forceinline__ float bf_lo(unsigned w) { return __uint_as_float(w << 16); }
; __device__ __forceinline__ float bf_hi(unsigned w) { return __uint_as_float(w & 0xffff0000u); }
;     __device__ __forceinline__ void operator()(const pg8::f32x4 (&acc)[2][2][4][2], const pg8::Unit& u, int wr, int wc, int fr, int fq) const {
;     ...
;                     if (GATE) { const v4u g = gq[m][bj];
;                         r[0] *= bf_lo(g.x); r[1] *= bf_hi(g.x); r[2] *= bf_lo(g.y); r[3] *= bf_hi(g.y); r[4] *= bf_lo(g.z); r[5] *= bf_hi(g.z); r[6] *= bf_lo(g.w); r[7] *= bf_hi(g.w); }
;                     if (ADD) { const v4u g = aq[m][bj];
;                         r[0] += bf_lo(g.x); r[1] += bf_hi(g.x); r[2] += bf_lo(g.y); r[3] += bf_hi(g.y); r[4] += bf_lo(g.z); r[5] += bf_hi(g.z); r[6] += bf_lo(g.w); r[7] += bf_hi(g.w); }
;                     if (PART) {
; #pragma unroll
;                         for (int j = 0; j < 8; ++j) s += r[j] * r[j];
;                     }
	v_lshlrev_b32_e32 v248, 16, v204
	v_and_b32_e32 v249, 0xffff0000, v204
	v_pk_mul_f32 v[76:77], v[76:77], v[248:249]
	v_lshlrev_b32_e32 v250, 16, v205
	v_and_b32_e32 v251, 0xffff0000, v205
	v_pk_mul_f32 v[78:79], v[78:79], v[250:251]
	v_lshlrev_b32_e32 v252, 16, v206
	v_and_b32_e32 v253, 0xffff0000, v206
	v_pk_mul_f32 v[72:73], v[72:73], v[252:253]
	v_lshlrev_b32_e32 v248, 16, v207
	v_and_b32_e32 v249, 0xffff0000, v207
	v_pk_mul_f32 v[74:75], v[74:75], v[248:249]
	v_lshlrev_b32_e32 v250, 16, v208
	v_and_b32_e32 v251, 0xffff0000, v208
	v_pk_mul_f32 v[68:69], v[68:69], v[250:251]
	v_lshlrev_b32_e32 v252, 16, v209
	v_and_b32_e32 v253, 0xffff0000, v209
	v_pk_mul_f32 v[70:71], v[70:71], v[252:253]
	v_lshlrev_b32_e32 v248, 16, v210
	v_and_b32_e32 v249, 0xffff0000, v210
	v_pk_mul_f32 v[64:65], v[64:65], v[248:249]
	v_lshlrev_b32_e32 v250, 16, v211
	v_and_b32_e32 v251, 0xffff0000, v211
	v_pk_mul_f32 v[66:67], v[66:67], v[250:251]
	v_pk_mul_f32 v[244:245], v[76:77], v[76:77]
	v_pk_fma_f32 v[244:245], v[78:79], v[78:79], v[244:245]
	v_pk_fma_f32 v[244:245], v[72:73], v[72:73], v[244:245]
	v_pk_fma_f32 v[244:245], v[74:75], v[74:75], v[244:245]
	v_pk_fma_f32 v[244:245], v[68:69], v[68:69], v[244:245]
	v_pk_fma_f32 v[244:245], v[70:71], v[70:71], v[244:245]
	v_pk_fma_f32 v[244:245], v[64:65], v[64:65], v[244:245]
	v_pk_fma_f32 v[244:245], v[66:67], v[66:67], v[244:245]
	v_add_f32_e32 v131, v244, v245
	s_waitcnt vmcnt(6)
	v_lshlrev_b32_e32 v248, 16, v212
	v_and_b32_e32 v249, 0xffff0000, v212
	v_pk_mul_f32 v[60:61], v[60:61], v[248:249]
	v_lshlrev_b32_e32 v250, 16, v213
	v_and_b32_e32 v251, 0xffff0000, v213
	v_pk_mul_f32 v[62:63], v[62:63], v[250:251]
	v_lshlrev_b32_e32 v252, 16, v214
	v_and_b32_e32 v253, 0xffff0000, v214
	v_pk_mul_f32 v[56:57], v[56:57], v[252:253]
	v_lshlrev_b32_e32 v248, 16, v215
	v_and_b32_e32 v249, 0xffff0000, v215
	v_pk_mul_f32 v[58:59], v[58:59], v[248:249]
	v_lshlrev_b32_e32 v250, 16, v216
	v_and_b32_e32 v251, 0xffff0000, v216
	v_pk_mul_f32 v[52:53], v[52:53], v[250:251]
	v_lshlrev_b32_e32 v252, 16, v217
	v_and_b32_e32 v253, 0xffff0000, v217
	v_pk_mul_f32 v[54:55], v[54:55], v[252:253]
	v_lshlrev_b32_e32 v248, 16, v218
	v_and_b32_e32 v249, 0xffff0000, v218
	v_pk_mul_f32 v[48:49], v[48:49], v[248:249]
	v_lshlrev_b32_e32 v250, 16, v219
	v_and_b32_e32 v251, 0xffff0000, v219
	v_pk_mul_f32 v[50:51], v[50:51], v[250:251]
	v_pk_mul_f32 v[244:245], v[60:61], v[60:61]
	v_pk_fma_f32 v[244:245], v[62:63], v[62:63], v[244:245]
	v_pk_fma_f32 v[244:245], v[56:57], v[56:57], v[244:245]
	v_pk_fma_f32 v[244:245], v[58:59], v[58:59], v[244:245]
	v_pk_fma_f32 v[244:245], v[52:53], v[52:53], v[244:245]
	v_pk_fma_f32 v[244:245], v[54:55], v[54:55], v[244:245]
	v_pk_fma_f32 v[244:245], v[48:49], v[48:49], v[244:245]
	v_pk_fma_f32 v[244:245], v[50:51], v[50:51], v[244:245]
	v_add_f32_e32 v132, v244, v245
	s_waitcnt vmcnt(4)
	v_lshlrev_b32_e32 v248, 16, v220
	v_and_b32_e32 v249, 0xffff0000, v220
	v_pk_mul_f32 v[44:45], v[44:45], v[248:249]
	v_lshlrev_b32_e32 v250, 16, v221
	v_and_b32_e32 v251, 0xffff0000, v221
	v_pk_mul_f32 v[46:47], v[46:47], v[250:251]
	v_lshlrev_b32_e32 v252, 16, v222
	v_and_b32_e32 v253, 0xffff0000, v222
	v_pk_mul_f32 v[40:41], v[40:41], v[252:253]
	v_lshlrev_b32_e32 v248, 16, v223
	v_and_b32_e32 v249, 0xffff0000, v223
	v_pk_mul_f32 v[42:43], v[42:43], v[248:249]
	v_lshlrev_b32_e32 v250, 16, v224
	v_and_b32_e32 v251, 0xffff0000, v224
	v_pk_mul_f32 v[36:37], v[36:37], v[250:251]
	v_lshlrev_b32_e32 v252, 16, v225
	v_and_b32_e32 v253, 0xffff0000, v225
	v_pk_mul_f32 v[38:39], v[38:39], v[252:253]
	v_lshlrev_b32_e32 v248, 16, v226
	v_and_b32_e32 v249, 0xffff0000, v226
	v_pk_mul_f32 v[32:33], v[32:33], v[248:249]
	v_lshlrev_b32_e32 v250, 16, v227
	v_and_b32_e32 v251, 0xffff0000, v227
	v_pk_mul_f32 v[34:35], v[34:35], v[250:251]
	v_pk_mul_f32 v[244:245], v[44:45], v[44:45]
	v_pk_fma_f32 v[244:245], v[46:47], v[46:47], v[244:245]
	v_pk_fma_f32 v[244:245], v[40:41], v[40:41], v[244:245]
	v_pk_fma_f32 v[244:245], v[42:43], v[42:43], v[244:245]
	v_pk_fma_f32 v[244:245], v[36:37], v[36:37], v[244:245]
	v_pk_fma_f32 v[244:245], v[38:39], v[38:39], v[244:245]
	v_pk_fma_f32 v[244:245], v[32:33], v[32:33], v[244:245]
	v_pk_fma_f32 v[244:245], v[34:35], v[34:35], v[244:245]
	v_add_f32_e32 v133, v244, v245
	s_waitcnt vmcnt(2)
; __device__ __forceinline__ float bf_lo(unsigned w) { return __uint_as_float(w << 16); }
; __device__ __forceinline__ float bf_hi(unsigned w) { return __uint_as_float(w & 0xffff0000u); }
; __device__ __forceinline__ unsigned pk2(float lo, float hi) { bf16x2_t r = __builtin_convertvector((f32x2_t){lo, hi}, bf16x2_t); return __builtin_bit_cast(unsigned, r); }
;     __device__ __forceinline__ void operator()(const pg8::f32x4 (&acc)[2][2][4][2], const pg8::Unit& u, int wr, int wc, int fr, int fq) const {
;     ...
;                     if (GATE) { const v4u g = gq[m][bj];
;                         r[0] *= bf_lo(g.x); r[1] *= bf_hi(g.x); r[2] *= bf_lo(g.y); r[3] *= bf_hi(g.y); r[4] *= bf_lo(g.z); r[5] *= bf_hi(g.z); r[6] *= bf_lo(g.w); r[7] *= bf_hi(g.w); }
;                     if (ADD) { const v4u g = aq[m][bj];
;                         r[0] += bf_lo(g.x); r[1] += bf_hi(g.x); r[2] += bf_lo(g.y); r[3] += bf_hi(g.y); r[4] += bf_lo(g.z); r[5] += bf_hi(g.z); r[6] += bf_lo(g.w); r[7] += bf_hi(g.w); }
;                     if (PART) {
; #pragma unroll
;                         for (int j = 0; j < 8; ++j) s += r[j] * r[j];
;                     }
;                     v4u w; w.x = pk2(r[0], r[1]); w.y = pk2(r[2], r[3]); w.z = pk2(r[4], r[5]); w.w = pk2(r[6], r[7]);
;                     st16_wt(O + off + bj * 128, w);
;                 }
;                 if (PART) { s += __shfl_xor(s, 16); s += __shfl_xor(s, 32); st4_wt(part + (size_t)row * 16 + u.pn * 4 + wc, s); }
	v_lshlrev_b32_e32 v248, 16, v228
	v_and_b32_e32 v249, 0xffff0000, v228
	v_pk_mul_f32 v[28:29], v[28:29], v[248:249]
	v_lshlrev_b32_e32 v250, 16, v229
	v_and_b32_e32 v251, 0xffff0000, v229
	v_pk_mul_f32 v[30:31], v[30:31], v[250:251]
	v_lshlrev_b32_e32 v252, 16, v230
	v_and_b32_e32 v253, 0xffff0000, v230
	v_pk_mul_f32 v[24:25], v[24:25], v[252:253]
	v_lshlrev_b32_e32 v248, 16, v231
	v_and_b32_e32 v249, 0xffff0000, v231
	v_pk_mul_f32 v[26:27], v[26:27], v[248:249]
	v_lshlrev_b32_e32 v250, 16, v232
	v_and_b32_e32 v251, 0xffff0000, v232
	v_pk_mul_f32 v[20:21], v[20:21], v[250:251]
	v_lshlrev_b32_e32 v252, 16, v233
	v_and_b32_e32 v253, 0xffff0000, v233
	v_pk_mul_f32 v[22:23], v[22:23], v[252:253]
	v_lshlrev_b32_e32 v248, 16, v234
	v_and_b32_e32 v249, 0xffff0000, v234
	v_pk_mul_f32 v[16:17], v[16:17], v[248:249]
	v_lshlrev_b32_e32 v250, 16, v235
	v_and_b32_e32 v251, 0xffff0000, v235
	v_pk_mul_f32 v[18:19], v[18:19], v[250:251]
	v_pk_mul_f32 v[244:245], v[28:29], v[28:29]
	v_pk_fma_f32 v[244:245], v[30:31], v[30:31], v[244:245]
	v_pk_fma_f32 v[244:245], v[24:25], v[24:25], v[244:245]
	v_pk_fma_f32 v[244:245], v[26:27], v[26:27], v[244:245]
	v_pk_fma_f32 v[244:245], v[20:21], v[20:21], v[244:245]
	v_pk_fma_f32 v[244:245], v[22:23], v[22:23], v[244:245]
	v_pk_fma_f32 v[244:245], v[16:17], v[16:17], v[244:245]
	v_pk_fma_f32 v[244:245], v[18:19], v[18:19], v[244:245]
	v_add_f32_e32 v134, v244, v245
	s_waitcnt vmcnt(0)
	v_lshlrev_b32_e32 v248, 16, v236
	v_and_b32_e32 v249, 0xffff0000, v236
	v_pk_mul_f32 v[12:13], v[12:13], v[248:249]
	v_lshlrev_b32_e32 v250, 16, v237
	v_and_b32_e32 v251, 0xffff0000, v237
	v_pk_mul_f32 v[14:15], v[14:15], v[250:251]
	v_lshlrev_b32_e32 v252, 16, v238
	v_and_b32_e32 v253, 0xffff0000, v238
	v_pk_mul_f32 v[8:9], v[8:9], v[252:253]
	v_lshlrev_b32_e32 v248, 16, v239
	v_and_b32_e32 v249, 0xffff0000, v239
	v_pk_mul_f32 v[10:11], v[10:11], v[248:249]
	v_lshlrev_b32_e32 v250, 16, v240
	v_and_b32_e32 v251, 0xffff0000, v240
	v_pk_mul_f32 v[4:5], v[4:5], v[250:251]
	v_lshlrev_b32_e32 v252, 16, v241
	v_and_b32_e32 v253, 0xffff0000, v241
	v_pk_mul_f32 v[6:7], v[6:7], v[252:253]
	v_lshlrev_b32_e32 v248, 16, v242
	v_and_b32_e32 v249, 0xffff0000, v242
	v_pk_mul_f32 v[0:1], v[0:1], v[248:249]
	v_lshlrev_b32_e32 v250, 16, v243
	v_and_b32_e32 v251, 0xffff0000, v243
	v_pk_mul_f32 v[2:3], v[2:3], v[250:251]
	v_pk_mul_f32 v[244:245], v[12:13], v[12:13]
	v_pk_fma_f32 v[244:245], v[14:15], v[14:15], v[244:245]
	v_pk_fma_f32 v[244:245], v[8:9], v[8:9], v[244:245]
	v_pk_fma_f32 v[244:245], v[10:11], v[10:11], v[244:245]
	v_pk_fma_f32 v[244:245], v[4:5], v[4:5], v[244:245]
	v_pk_fma_f32 v[244:245], v[6:7], v[6:7], v[244:245]
	v_pk_fma_f32 v[244:245], v[0:1], v[0:1], v[244:245]
	v_pk_fma_f32 v[244:245], v[2:3], v[2:3], v[244:245]
	v_add_f32_e32 v135, v244, v245
	s_nop 1
	ds_bpermute_b32 v158, v177, v128
	ds_bpermute_b32 v159, v177, v129
	ds_bpermute_b32 v160, v177, v130
	ds_bpermute_b32 v161, v177, v131
	ds_bpermute_b32 v162, v177, v132
	ds_bpermute_b32 v163, v177, v133
	ds_bpermute_b32 v164, v177, v134
	ds_bpermute_b32 v165, v177, v135
	s_waitcnt lgkmcnt(0)
	v_add_f32_e32 v128, v128, v158
	v_add_f32_e32 v129, v129, v159
	v_add_f32_e32 v130, v130, v160
	v_add_f32_e32 v131, v131, v161
	v_add_f32_e32 v132, v132, v162
	v_add_f32_e32 v133, v133, v163
	v_add_f32_e32 v134, v134, v164
	v_add_f32_e32 v135, v135, v165
	s_nop 1
	ds_bpermute_b32 v158, v155, v128
	ds_bpermute_b32 v159, v155, v129
	ds_bpermute_b32 v160, v155, v130
	ds_bpermute_b32 v161, v155, v131
	ds_bpermute_b32 v162, v155, v132
	ds_bpermute_b32 v163, v155, v133
	ds_bpermute_b32 v164, v155, v134
	ds_bpermute_b32 v165, v155, v135
	s_waitcnt lgkmcnt(0)
	v_add_f32_e32 v128, v128, v158
	v_add_f32_e32 v129, v129, v159
	v_add_f32_e32 v130, v130, v160
	v_add_f32_e32 v131, v131, v161
	v_add_f32_e32 v132, v132, v162
	v_add_f32_e32 v133, v133, v163
	v_add_f32_e32 v134, v134, v164
	v_add_f32_e32 v135, v135, v165
	global_store_dword v153, v128, s[20:21]
	v_add_u32_e32 v159, 0x400, v153
	global_store_dword v159, v129, s[20:21]
	v_add_u32_e32 v160, 0x800, v153
	global_store_dword v160, v130, s[20:21]
	v_add_u32_e32 v161, 0xc00, v153
	global_store_dword v161, v131, s[20:21]
	v_add_u32_e32 v162, 0x2000, v153
	global_store_dword v162, v132, s[20:21]
	v_add_u32_e32 v163, 0x2400, v153
	global_store_dword v163, v133, s[20:21]
	v_add_u32_e32 v164, 0x2800, v153
	global_store_dword v164, v134, s[20:21]
	v_add_u32_e32 v165, 0x2c00, v153
	global_store_dword v165, v135, s[20:21]
	s_waitcnt vmcnt(0)
	s_barrier
	v_readfirstlane_b32 s59, v195
	s_cmp_lg_u32 s59, 0
	s_cbranch_scc1 .Lp13_bskip
	s_mov_b64 exec, 1
	s_and_b32 s59, s2, 7
	s_lshl_b32 s59, s59, 3
	s_bfe_u32 s60, s2, 0x30003
	s_or_b32 s59, s59, s60
	s_lshl_b32 s59, s59, 5
	s_add_u32 s60, s28, 0x3903600
	s_addc_u32 s61, s29, 0
	v_mov_b32_e32 v244, s59
	v_mov_b32_e32 v245, 1
	s_cmp_eq_u32 s99, 1
	s_cbranch_scc1 .Lp13_bfast
	buffer_wbl2 sc1
	s_waitcnt vmcnt(0)
.Lp13_bfast:
	global_atomic_add v246, v244, v245, s[60:61] offset:8 sc0
	buffer_inv sc1
	s_waitcnt vmcnt(0)
	v_lshrrev_b32_e32 v246, 2, v246
	v_add_u32_e32 v246, 1, v246
	v_lshlrev_b32_e32 v246, 2, v246
	s_mov_b32 s59, 0
.Lp13_bspin:
	global_load_dword v247, v244, s[60:61] offset:8 sc1
	s_waitcnt vmcnt(0)
	v_cmp_ge_u32_e32 vcc, v247, v246
	s_cbranch_vccnz .Lp13_bdone
	s_sleep 1
	s_add_u32 s59, s59, 1
	s_cmp_lt_u32 s59, 0x400000
	s_cbranch_scc1 .Lp13_bspin
.Lp13_bdone:
	s_cmp_eq_u32 s99, 1
	s_cbranch_scc1 .Lp13_bacq
	buffer_inv sc1
	s_waitcnt vmcnt(0)

; __device__ __forceinline__ float bf_lo(unsigned w) { return __uint_as_float(w << 16); }
; __device__ __forceinline__ float bf_hi(unsigned w) { return __uint_as_float(w & 0xffff0000u); }
; template <bool SRC_F32, int R> __device__ __forceinline__ void ew_load(EwSet<SRC_F32, R>& S, int rb, const float* hsrc32, const bf16* hsrcb, const bf16* f, const float* part, int lane) {
;     ...
;     for (int i = 0; i < R; ++i) S.p[i] = (lane < 16) ? part[(size_t)(rb + i) * 16 + lane] : 0.f;
; #pragma unroll
;     for (int i = 0; i < R; ++i)
; #pragma unroll
;         for (int j = 0; j < 4; ++j) {
;             S.fw[i][j] = ((const v2u*)(f + (size_t)(rb + i) * D) + lane)[64 * j];
;             if constexpr (SRC_F32) S.h32[i][j] = __builtin_nontemporal_load((const f32x4*)(hsrc32 + (size_t)(rb + i) * D) + lane + 64 * j);
;             else S.hb[i][j] = ((const v2u*)(hsrcb + (size_t)(rb + i) * D) + lane)[64 * j];
;         }
; }
; template <bool SRC_F32, bool FINAL, int R> __device__ __forceinline__ void ew_compute(const EwSet<SRC_F32, R>& S, int rb, const f32x4 (&g)[4], bf16* hb_out, float* out32, float scale, float* rs_out, int lane) {
; #pragma unroll
;     for (int i = 0; i < R; ++i) {
;         float q = S.p[i];
;         q += __shfl_xor(q, 1); q += __shfl_xor(q, 2); q += __shfl_xor(q, 4); q += __shfl_xor(q, 8);
;         const float ss = __shfl(q, 0);
;         const float rs = scale / sqrtf(ss * (1.f / D) + EPS);
;         float s2 = 0.f;
; #pragma unroll
;         for (int j = 0; j < 4; ++j) {
;             f32x4 h;
;             if constexpr (SRC_F32) h = S.h32[i][j];
;             else { const v2u hw = S.hb[i][j]; h.x = bf_lo(hw.x); h.y = bf_hi(hw.x); h.z = bf_lo(hw.y); h.w = bf_hi(hw.y); }
;             const v2u fw = S.fw[i][j];
;             f32x4 v; v.x = h.x + bf_lo(fw.x) * rs * g[j].x; v.y = h.y + bf_hi(fw.x) * rs * g[j].y; v.z = h.z + bf_lo(fw.y) * rs * g[j].z; v.w = h.w + bf_hi(fw.y) * rs * g[j].w;
;             if (FINAL) __builtin_nontemporal_store(v, (f32x4*)(out32 + (size_t)(rb + i) * D) + lane + 64 * j);
.Lp13_bskip:
	s_barrier
	s_add_u32 s60, s84, 0xffffff10
	s_addc_u32 s61, s85, -1
	s_load_dwordx2 s[62:63], s[60:61], 0xd0
	s_load_dwordx2 s[64:65], s[60:61], 0xd8
	s_add_u32 s66, s28, 0x5000000
	s_addc_u32 s67, s29, 0
	v_lshl_add_u32 v165, v154, 6, v157
	global_load_dwordx4 v[196:199], v165, s[20:21]
	v_add_u32_e32 v163, 0x400, v165
	global_load_dwordx4 v[200:203], v163, s[20:21]
	v_add_u32_e32 v163, 0x800, v165
	global_load_dwordx4 v[204:207], v163, s[20:21]
	v_add_u32_e32 v163, 0xc00, v165
	global_load_dwordx4 v[208:211], v163, s[20:21]
	v_add_u32_e32 v163, 0x2000, v165
	global_load_dwordx4 v[212:215], v163, s[20:21]
	v_add_u32_e32 v163, 0x2400, v165
	global_load_dwordx4 v[216:219], v163, s[20:21]
	v_add_u32_e32 v163, 0x2800, v165
	global_load_dwordx4 v[220:223], v163, s[20:21]
	v_add_u32_e32 v163, 0x2c00, v165
	global_load_dwordx4 v[224:227], v163, s[20:21]
	global_load_dwordx4 v[178:181], v152, s[66:67]
	global_load_dwordx4 v[182:185], v152, s[66:67] offset:256
	v_add_u32_e32 v159, 0x8000, v152
	global_load_dwordx4 v[186:189], v159, s[66:67]
	global_load_dwordx4 v[190:193], v159, s[66:67] offset:256
	s_waitcnt lgkmcnt(0)
	global_load_dwordx4 v[228:231], v156, s[62:63]
	global_load_dwordx4 v[232:235], v156, s[62:63] offset:16
	global_load_dwordx4 v[236:239], v156, s[62:63] offset:512
	global_load_dwordx4 v[240:243], v156, s[62:63] offset:528
	s_waitcnt vmcnt(8)
	v_add_f32_e32 v128, v196, v197
	v_add_f32_e32 v128, v198, v128
	v_add_f32_e32 v128, v199, v128
	v_add_f32_e32 v129, v200, v201
	v_add_f32_e32 v129, v202, v129
	v_add_f32_e32 v129, v203, v129
	v_add_f32_e32 v130, v204, v205
	v_add_f32_e32 v130, v206, v130
	v_add_f32_e32 v130, v207, v130
	v_add_f32_e32 v131, v208, v209
	v_add_f32_e32 v131, v210, v131
	v_add_f32_e32 v131, v211, v131
	v_add_f32_e32 v132, v212, v213
	v_add_f32_e32 v132, v214, v132
	v_add_f32_e32 v132, v215, v132
	v_add_f32_e32 v133, v216, v217
	v_add_f32_e32 v133, v218, v133
	v_add_f32_e32 v133, v219, v133
	v_add_f32_e32 v134, v220, v221
	v_add_f32_e32 v134, v222, v134
	v_add_f32_e32 v134, v223, v134
	v_add_f32_e32 v135, v224, v225
	v_add_f32_e32 v135, v226, v135
	v_add_f32_e32 v135, v227, v135
	s_nop 1
	ds_bpermute_b32 v248, v177, v128
	ds_bpermute_b32 v249, v177, v129
	ds_bpermute_b32 v250, v177, v130
	ds_bpermute_b32 v251, v177, v131
	ds_bpermute_b32 v252, v177, v132
	ds_bpermute_b32 v253, v177, v133
	ds_bpermute_b32 v247, v177, v134
	ds_bpermute_b32 v245, v177, v135
	s_waitcnt lgkmcnt(0)
	v_add_f32_e32 v128, v128, v248
	v_add_f32_e32 v129, v129, v249
	v_add_f32_e32 v130, v130, v250
	v_add_f32_e32 v131, v131, v251
	v_add_f32_e32 v132, v132, v252
	v_add_f32_e32 v133, v133, v253
	v_add_f32_e32 v134, v134, v247
	v_add_f32_e32 v135, v135, v245
	s_nop 1
	ds_bpermute_b32 v248, v155, v128
	ds_bpermute_b32 v249, v155, v129
	ds_bpermute_b32 v250, v155, v130
	ds_bpermute_b32 v251, v155, v131
	ds_bpermute_b32 v252, v155, v132
	ds_bpermute_b32 v253, v155, v133
	ds_bpermute_b32 v247, v155, v134
	ds_bpermute_b32 v245, v155, v135
	s_waitcnt lgkmcnt(0)
	v_add_f32_e32 v128, v128, v248
	v_add_f32_e32 v129, v129, v249
	v_add_f32_e32 v130, v130, v250
	v_add_f32_e32 v131, v131, v251
	v_add_f32_e32 v132, v132, v252
	v_add_f32_e32 v133, v133, v253
	v_add_f32_e32 v134, v134, v247
	v_add_f32_e32 v135, v135, v245
	v_mul_f32_e32 v128, 0x3a800000, v128
	v_mul_f32_e32 v129, 0x3a800000, v129
	v_mul_f32_e32 v130, 0x3a800000, v130
	v_mul_f32_e32 v131, 0x3a800000, v131
	v_mul_f32_e32 v132, 0x3a800000, v132
	v_mul_f32_e32 v133, 0x3a800000, v133
	v_mul_f32_e32 v134, 0x3a800000, v134
	v_mul_f32_e32 v135, 0x3a800000, v135
	v_add_f32_e32 v128, 0x358637bd, v128
	v_add_f32_e32 v129, 0x358637bd, v129
	v_add_f32_e32 v130, 0x358637bd, v130
	v_add_f32_e32 v131, 0x358637bd, v131
	v_add_f32_e32 v132, 0x358637bd, v132
	v_add_f32_e32 v133, 0x358637bd, v133
	v_add_f32_e32 v134, 0x358637bd, v134
	v_add_f32_e32 v135, 0x358637bd, v135
	v_rsq_f32_e32 v158, v128
	v_rsq_f32_e32 v160, v129
	v_rsq_f32_e32 v162, v130
	v_rsq_f32_e32 v164, v131
	v_rsq_f32_e32 v166, v132
	v_rsq_f32_e32 v168, v133
	v_rsq_f32_e32 v244, v134
	v_rsq_f32_e32 v246, v135
	s_nop 0
	v_add_u32_e32 v159, 0x10000, v152
	global_load_dwordx4 v[196:199], v159, s[66:67]
	global_load_dwordx4 v[200:203], v159, s[66:67] offset:256
	v_add_u32_e32 v159, 0x18000, v152
	global_load_dwordx4 v[204:207], v159, s[66:67]
	global_load_dwordx4 v[208:211], v159, s[66:67] offset:256
	v_add_u32_e32 v159, 0x40000, v152
	global_load_dwordx4 v[212:215], v159, s[66:67]
	global_load_dwordx4 v[216:219], v159, s[66:67] offset:256
	v_add_u32_e32 v159, 0x48000, v152
	global_load_dwordx4 v[220:223], v159, s[66:67]
	global_load_dwordx4 v[224:227], v159, s[66:67] offset:256
	s_waitcnt vmcnt(8)
	v_lshlrev_b32_e32 v248, 16, v178
	v_and_b32_e32 v249, 0xffff0000, v178
	v_pk_mul_f32 v[124:125], v[124:125], v[158:159] op_sel_hi:[1,0]
	v_pk_fma_f32 v[124:125], v[124:125], v[228:229], v[248:249]
	v_lshlrev_b32_e32 v250, 16, v179
	v_and_b32_e32 v251, 0xffff0000, v179
	v_pk_mul_f32 v[126:127], v[126:127], v[158:159] op_sel_hi:[1,0]
	v_pk_fma_f32 v[126:127], v[126:127], v[230:231], v[250:251]
	v_lshlrev_b32_e32 v252, 16, v180
	v_and_b32_e32 v253, 0xffff0000, v180
	v_pk_mul_f32 v[120:121], v[120:121], v[158:159] op_sel_hi:[1,0]
	v_pk_fma_f32 v[120:121], v[120:121], v[232:233], v[252:253]
	v_lshlrev_b32_e32 v248, 16, v181
	v_and_b32_e32 v249, 0xffff0000, v181
	v_pk_mul_f32 v[122:123], v[122:123], v[158:159] op_sel_hi:[1,0]
	v_pk_fma_f32 v[122:123], v[122:123], v[234:235], v[248:249]
	v_lshlrev_b32_e32 v250, 16, v182
	v_and_b32_e32 v251, 0xffff0000, v182
	v_pk_mul_f32 v[116:117], v[116:117], v[158:159] op_sel_hi:[1,0]
	v_pk_fma_f32 v[116:117], v[116:117], v[236:237], v[250:251]
	v_lshlrev_b32_e32 v252, 16, v183
	v_and_b32_e32 v253, 0xffff0000, v183
	v_pk_mul_f32 v[118:119], v[118:119], v[158:159] op_sel_hi:[1,0]
	v_pk_fma_f32 v[118:119], v[118:119], v[238:239], v[252:253]
	v_lshlrev_b32_e32 v248, 16, v184
	v_and_b32_e32 v249, 0xffff0000, v184
	v_pk_mul_f32 v[112:113], v[112:113], v[158:159] op_sel_hi:[1,0]
	v_pk_fma_f32 v[112:113], v[112:113], v[240:241], v[248:249]
	v_lshlrev_b32_e32 v250, 16, v185
	v_and_b32_e32 v251, 0xffff0000, v185
	v_pk_mul_f32 v[114:115], v[114:115], v[158:159] op_sel_hi:[1,0]
	v_pk_fma_f32 v[114:115], v[114:115], v[242:243], v[250:251]
	v_lshlrev_b32_e32 v161, 1, v152
	global_store_dwordx4 v161, v[124:127], s[64:65] nt
	global_store_dwordx4 v161, v[120:123], s[64:65] offset:16 nt
	global_store_dwordx4 v161, v[116:119], s[64:65] offset:512 nt
	global_store_dwordx4 v161, v[112:115], s[64:65] offset:528 nt
	s_waitcnt vmcnt(12)
; __device__ __forceinline__ float bf_lo(unsigned w) { return __uint_as_float(w << 16); }
; __device__ __forceinline__ float bf_hi(unsigned w) { return __uint_as_float(w & 0xffff0000u); }
; template <bool SRC_F32, bool FINAL, int R> __device__ __forceinline__ void ew_compute(const EwSet<SRC_F32, R>& S, int rb, const f32x4 (&g)[4], bf16* hb_out, float* out32, float scale, float* rs_out, int lane) {
;     ...
; #pragma unroll
;         for (int j = 0; j < 4; ++j) {
;             f32x4 h;
;             if constexpr (SRC_F32) h = S.h32[i][j];
;             else { const v2u hw = S.hb[i][j]; h.x = bf_lo(hw.x); h.y = bf_hi(hw.x); h.z = bf_lo(hw.y); h.w = bf_hi(hw.y); }
;             const v2u fw = S.fw[i][j];
;             f32x4 v; v.x = h.x + bf_lo(fw.x) * rs * g[j].x; v.y = h.y + bf_hi(fw.x) * rs * g[j].y; v.z = h.z + bf_lo(fw.y) * rs * g[j].z; v.w = h.w + bf_hi(fw.y) * rs * g[j].w;
;             if (FINAL) __builtin_nontemporal_store(v, (f32x4*)(out32 + (size_t)(rb + i) * D) + lane + 64 * j);
	v_lshlrev_b32_e32 v248, 16, v186
	v_and_b32_e32 v249, 0xffff0000, v186
	v_pk_mul_f32 v[108:109], v[108:109], v[160:161] op_sel_hi:[1,0]
	v_pk_fma_f32 v[108:109], v[108:109], v[228:229], v[248:249]
	v_lshlrev_b32_e32 v250, 16, v187
	v_and_b32_e32 v251, 0xffff0000, v187
	v_pk_mul_f32 v[110:111], v[110:111], v[160:161] op_sel_hi:[1,0]
	v_pk_fma_f32 v[110:111], v[110:111], v[230:231], v[250:251]
	v_lshlrev_b32_e32 v252, 16, v188
	v_and_b32_e32 v253, 0xffff0000, v188
	v_pk_mul_f32 v[104:105], v[104:105], v[160:161] op_sel_hi:[1,0]
	v_pk_fma_f32 v[104:105], v[104:105], v[232:233], v[252:253]
	v_lshlrev_b32_e32 v248, 16, v189
	v_and_b32_e32 v249, 0xffff0000, v189
	v_pk_mul_f32 v[106:107], v[106:107], v[160:161] op_sel_hi:[1,0]
	v_pk_fma_f32 v[106:107], v[106:107], v[234:235], v[248:249]
	v_lshlrev_b32_e32 v250, 16, v190
	v_and_b32_e32 v251, 0xffff0000, v190
	v_pk_mul_f32 v[100:101], v[100:101], v[160:161] op_sel_hi:[1,0]
	v_pk_fma_f32 v[100:101], v[100:101], v[236:237], v[250:251]
	v_lshlrev_b32_e32 v252, 16, v191
	v_and_b32_e32 v253, 0xffff0000, v191
	v_pk_mul_f32 v[102:103], v[102:103], v[160:161] op_sel_hi:[1,0]
	v_pk_fma_f32 v[102:103], v[102:103], v[238:239], v[252:253]
	v_lshlrev_b32_e32 v248, 16, v192
	v_and_b32_e32 v249, 0xffff0000, v192
	v_pk_mul_f32 v[96:97], v[96:97], v[160:161] op_sel_hi:[1,0]
	v_pk_fma_f32 v[96:97], v[96:97], v[240:241], v[248:249]
	v_lshlrev_b32_e32 v250, 16, v193
	v_and_b32_e32 v251, 0xffff0000, v193
	v_pk_mul_f32 v[98:99], v[98:99], v[160:161] op_sel_hi:[1,0]
	v_pk_fma_f32 v[98:99], v[98:99], v[242:243], v[250:251]
	v_add_u32_e32 v161, 0x8000, v152
	v_lshlrev_b32_e32 v161, 1, v161
	global_store_dwordx4 v161, v[108:111], s[64:65] nt
	global_store_dwordx4 v161, v[104:107], s[64:65] offset:16 nt
	global_store_dwordx4 v161, v[100:103], s[64:65] offset:512 nt
	global_store_dwordx4 v161, v[96:99], s[64:65] offset:528 nt
	v_add_u32_e32 v159, 0x50000, v152
	global_load_dwordx4 v[178:181], v159, s[66:67]
	global_load_dwordx4 v[182:185], v159, s[66:67] offset:256
	v_add_u32_e32 v159, 0x58000, v152
	global_load_dwordx4 v[186:189], v159, s[66:67]
	global_load_dwordx4 v[190:193], v159, s[66:67] offset:256
	s_waitcnt vmcnt(18)
	v_lshlrev_b32_e32 v248, 16, v196
	v_and_b32_e32 v249, 0xffff0000, v196
	v_pk_mul_f32 v[92:93], v[92:93], v[162:163] op_sel_hi:[1,0]
	v_pk_fma_f32 v[92:93], v[92:93], v[228:229], v[248:249]
	v_lshlrev_b32_e32 v250, 16, v197
	v_and_b32_e32 v251, 0xffff0000, v197
	v_pk_mul_f32 v[94:95], v[94:95], v[162:163] op_sel_hi:[1,0]
	v_pk_fma_f32 v[94:95], v[94:95], v[230:231], v[250:251]
	v_lshlrev_b32_e32 v252, 16, v198
	v_and_b32_e32 v253, 0xffff0000, v198
	v_pk_mul_f32 v[88:89], v[88:89], v[162:163] op_sel_hi:[1,0]
	v_pk_fma_f32 v[88:89], v[88:89], v[232:233], v[252:253]
	v_lshlrev_b32_e32 v248, 16, v199
	v_and_b32_e32 v249, 0xffff0000, v199
	v_pk_mul_f32 v[90:91], v[90:91], v[162:163] op_sel_hi:[1,0]
	v_pk_fma_f32 v[90:91], v[90:91], v[234:235], v[248:249]
	v_lshlrev_b32_e32 v250, 16, v200
	v_and_b32_e32 v251, 0xffff0000, v200
	v_pk_mul_f32 v[84:85], v[84:85], v[162:163] op_sel_hi:[1,0]
	v_pk_fma_f32 v[84:85], v[84:85], v[236:237], v[250:251]
	v_lshlrev_b32_e32 v252, 16, v201
	v_and_b32_e32 v253, 0xffff0000, v201
	v_pk_mul_f32 v[86:87], v[86:87], v[162:163] op_sel_hi:[1,0]
	v_pk_fma_f32 v[86:87], v[86:87], v[238:239], v[252:253]
	v_lshlrev_b32_e32 v248, 16, v202
	v_and_b32_e32 v249, 0xffff0000, v202
	v_pk_mul_f32 v[80:81], v[80:81], v[162:163] op_sel_hi:[1,0]
	v_pk_fma_f32 v[80:81], v[80:81], v[240:241], v[248:249]
	v_lshlrev_b32_e32 v250, 16, v203
	v_and_b32_e32 v251, 0xffff0000, v203
	v_pk_mul_f32 v[82:83], v[82:83], v[162:163] op_sel_hi:[1,0]
	v_pk_fma_f32 v[82:83], v[82:83], v[242:243], v[250:251]
	v_add_u32_e32 v161, 0x10000, v152
	v_lshlrev_b32_e32 v161, 1, v161
	global_store_dwordx4 v161, v[92:95], s[64:65] nt
	global_store_dwordx4 v161, v[88:91], s[64:65] offset:16 nt
	global_store_dwordx4 v161, v[84:87], s[64:65] offset:512 nt
	global_store_dwordx4 v161, v[80:83], s[64:65] offset:528 nt
	s_waitcnt vmcnt(20)
	v_lshlrev_b32_e32 v248, 16, v204
	v_and_b32_e32 v249, 0xffff0000, v204
	v_pk_mul_f32 v[76:77], v[76:77], v[164:165] op_sel_hi:[1,0]
	v_pk_fma_f32 v[76:77], v[76:77], v[228:229], v[248:249]
	v_lshlrev_b32_e32 v250, 16, v205
	v_and_b32_e32 v251, 0xffff0000, v205
	v_pk_mul_f32 v[78:79], v[78:79], v[164:165] op_sel_hi:[1,0]
	v_pk_fma_f32 v[78:79], v[78:79], v[230:231], v[250:251]
	v_lshlrev_b32_e32 v252, 16, v206
	v_and_b32_e32 v253, 0xffff0000, v206
	v_pk_mul_f32 v[72:73], v[72:73], v[164:165] op_sel_hi:[1,0]
	v_pk_fma_f32 v[72:73], v[72:73], v[232:233], v[252:253]
	v_lshlrev_b32_e32 v248, 16, v207
	v_and_b32_e32 v249, 0xffff0000, v207
	v_pk_mul_f32 v[74:75], v[74:75], v[164:165] op_sel_hi:[1,0]
	v_pk_fma_f32 v[74:75], v[74:75], v[234:235], v[248:249]
	v_lshlrev_b32_e32 v250, 16, v208
	v_and_b32_e32 v251, 0xffff0000, v208
	v_pk_mul_f32 v[68:69], v[68:69], v[164:165] op_sel_hi:[1,0]
	v_pk_fma_f32 v[68:69], v[68:69], v[236:237], v[250:251]
	v_lshlrev_b32_e32 v252, 16, v209
	v_and_b32_e32 v253, 0xffff0000, v209
	v_pk_mul_f32 v[70:71], v[70:71], v[164:165] op_sel_hi:[1,0]
	v_pk_fma_f32 v[70:71], v[70:71], v[238:239], v[252:253]
	v_lshlrev_b32_e32 v248, 16, v210
	v_and_b32_e32 v249, 0xffff0000, v210
	v_pk_mul_f32 v[64:65], v[64:65], v[164:165] op_sel_hi:[1,0]
	v_pk_fma_f32 v[64:65], v[64:65], v[240:241], v[248:249]
	v_lshlrev_b32_e32 v250, 16, v211
	v_and_b32_e32 v251, 0xffff0000, v211
	v_pk_mul_f32 v[66:67], v[66:67], v[164:165] op_sel_hi:[1,0]
	v_pk_fma_f32 v[66:67], v[66:67], v[242:243], v[250:251]
	v_add_u32_e32 v161, 0x18000, v152
	v_lshlrev_b32_e32 v161, 1, v161
	global_store_dwordx4 v161, v[76:79], s[64:65] nt
	global_store_dwordx4 v161, v[72:75], s[64:65] offset:16 nt
	global_store_dwordx4 v161, v[68:71], s[64:65] offset:512 nt
	global_store_dwordx4 v161, v[64:67], s[64:65] offset:528 nt
	s_waitcnt vmcnt(22)
; __device__ __forceinline__ float bf_lo(unsigned w) { return __uint_as_float(w << 16); }
; __device__ __forceinline__ float bf_hi(unsigned w) { return __uint_as_float(w & 0xffff0000u); }
; template <bool SRC_F32, bool FINAL, int R> __device__ __forceinline__ void ew_compute(const EwSet<SRC_F32, R>& S, int rb, const f32x4 (&g)[4], bf16* hb_out, float* out32, float scale, float* rs_out, int lane) {
;     ...
; #pragma unroll
;         for (int j = 0; j < 4; ++j) {
;             f32x4 h;
;             if constexpr (SRC_F32) h = S.h32[i][j];
;             else { const v2u hw = S.hb[i][j]; h.x = bf_lo(hw.x); h.y = bf_hi(hw.x); h.z = bf_lo(hw.y); h.w = bf_hi(hw.y); }
;             const v2u fw = S.fw[i][j];
;             f32x4 v; v.x = h.x + bf_lo(fw.x) * rs * g[j].x; v.y = h.y + bf_hi(fw.x) * rs * g[j].y; v.z = h.z + bf_lo(fw.y) * rs * g[j].z; v.w = h.w + bf_hi(fw.y) * rs * g[j].w;
;             if (FINAL) __builtin_nontemporal_store(v, (f32x4*)(out32 + (size_t)(rb + i) * D) + lane + 64 * j);
	v_lshlrev_b32_e32 v248, 16, v212
	v_and_b32_e32 v249, 0xffff0000, v212
	v_pk_mul_f32 v[60:61], v[60:61], v[166:167] op_sel_hi:[1,0]
	v_pk_fma_f32 v[60:61], v[60:61], v[228:229], v[248:249]
	v_lshlrev_b32_e32 v250, 16, v213
	v_and_b32_e32 v251, 0xffff0000, v213
	v_pk_mul_f32 v[62:63], v[62:63], v[166:167] op_sel_hi:[1,0]
	v_pk_fma_f32 v[62:63], v[62:63], v[230:231], v[250:251]
	v_lshlrev_b32_e32 v252, 16, v214
	v_and_b32_e32 v253, 0xffff0000, v214
	v_pk_mul_f32 v[56:57], v[56:57], v[166:167] op_sel_hi:[1,0]
	v_pk_fma_f32 v[56:57], v[56:57], v[232:233], v[252:253]
	v_lshlrev_b32_e32 v248, 16, v215
	v_and_b32_e32 v249, 0xffff0000, v215
	v_pk_mul_f32 v[58:59], v[58:59], v[166:167] op_sel_hi:[1,0]
	v_pk_fma_f32 v[58:59], v[58:59], v[234:235], v[248:249]
	v_lshlrev_b32_e32 v250, 16, v216
	v_and_b32_e32 v251, 0xffff0000, v216
	v_pk_mul_f32 v[52:53], v[52:53], v[166:167] op_sel_hi:[1,0]
	v_pk_fma_f32 v[52:53], v[52:53], v[236:237], v[250:251]
	v_lshlrev_b32_e32 v252, 16, v217
	v_and_b32_e32 v253, 0xffff0000, v217
	v_pk_mul_f32 v[54:55], v[54:55], v[166:167] op_sel_hi:[1,0]
	v_pk_fma_f32 v[54:55], v[54:55], v[238:239], v[252:253]
	v_lshlrev_b32_e32 v248, 16, v218
	v_and_b32_e32 v249, 0xffff0000, v218
	v_pk_mul_f32 v[48:49], v[48:49], v[166:167] op_sel_hi:[1,0]
	v_pk_fma_f32 v[48:49], v[48:49], v[240:241], v[248:249]
	v_lshlrev_b32_e32 v250, 16, v219
	v_and_b32_e32 v251, 0xffff0000, v219
	v_pk_mul_f32 v[50:51], v[50:51], v[166:167] op_sel_hi:[1,0]
	v_pk_fma_f32 v[50:51], v[50:51], v[242:243], v[250:251]
	v_add_u32_e32 v161, 0x40000, v152
	v_lshlrev_b32_e32 v161, 1, v161
	global_store_dwordx4 v161, v[60:63], s[64:65] nt
	global_store_dwordx4 v161, v[56:59], s[64:65] offset:16 nt
	global_store_dwordx4 v161, v[52:55], s[64:65] offset:512 nt
	global_store_dwordx4 v161, v[48:51], s[64:65] offset:528 nt
	s_waitcnt vmcnt(24)
	v_lshlrev_b32_e32 v248, 16, v220
	v_and_b32_e32 v249, 0xffff0000, v220
	v_pk_mul_f32 v[44:45], v[44:45], v[168:169] op_sel_hi:[1,0]
	v_pk_fma_f32 v[44:45], v[44:45], v[228:229], v[248:249]
	v_lshlrev_b32_e32 v250, 16, v221
	v_and_b32_e32 v251, 0xffff0000, v221
	v_pk_mul_f32 v[46:47], v[46:47], v[168:169] op_sel_hi:[1,0]
	v_pk_fma_f32 v[46:47], v[46:47], v[230:231], v[250:251]
	v_lshlrev_b32_e32 v252, 16, v222
	v_and_b32_e32 v253, 0xffff0000, v222
	v_pk_mul_f32 v[40:41], v[40:41], v[168:169] op_sel_hi:[1,0]
	v_pk_fma_f32 v[40:41], v[40:41], v[232:233], v[252:253]
	v_lshlrev_b32_e32 v248, 16, v223
	v_and_b32_e32 v249, 0xffff0000, v223
	v_pk_mul_f32 v[42:43], v[42:43], v[168:169] op_sel_hi:[1,0]
	v_pk_fma_f32 v[42:43], v[42:43], v[234:235], v[248:249]
	v_lshlrev_b32_e32 v250, 16, v224
	v_and_b32_e32 v251, 0xffff0000, v224
	v_pk_mul_f32 v[36:37], v[36:37], v[168:169] op_sel_hi:[1,0]
	v_pk_fma_f32 v[36:37], v[36:37], v[236:237], v[250:251]
	v_lshlrev_b32_e32 v252, 16, v225
	v_and_b32_e32 v253, 0xffff0000, v225
	v_pk_mul_f32 v[38:39], v[38:39], v[168:169] op_sel_hi:[1,0]
	v_pk_fma_f32 v[38:39], v[38:39], v[238:239], v[252:253]
	v_lshlrev_b32_e32 v248, 16, v226
	v_and_b32_e32 v249, 0xffff0000, v226
	v_pk_mul_f32 v[32:33], v[32:33], v[168:169] op_sel_hi:[1,0]
	v_pk_fma_f32 v[32:33], v[32:33], v[240:241], v[248:249]
	v_lshlrev_b32_e32 v250, 16, v227
	v_and_b32_e32 v251, 0xffff0000, v227
	v_pk_mul_f32 v[34:35], v[34:35], v[168:169] op_sel_hi:[1,0]
	v_pk_fma_f32 v[34:35], v[34:35], v[242:243], v[250:251]
	v_add_u32_e32 v161, 0x48000, v152
	v_lshlrev_b32_e32 v161, 1, v161
	global_store_dwordx4 v161, v[44:47], s[64:65] nt
	global_store_dwordx4 v161, v[40:43], s[64:65] offset:16 nt
	global_store_dwordx4 v161, v[36:39], s[64:65] offset:512 nt
	global_store_dwordx4 v161, v[32:35], s[64:65] offset:528 nt
	s_waitcnt vmcnt(18)
; __device__ __forceinline__ float bf_lo(unsigned w) { return __uint_as_float(w << 16); }
; __device__ __forceinline__ float bf_hi(unsigned w) { return __uint_as_float(w & 0xffff0000u); }
; template <bool SRC_F32, bool FINAL, int R> __device__ __forceinline__ void ew_compute(const EwSet<SRC_F32, R>& S, int rb, const f32x4 (&g)[4], bf16* hb_out, float* out32, float scale, float* rs_out, int lane) {
;     ...
; #pragma unroll
;         for (int j = 0; j < 4; ++j) {
;             f32x4 h;
;             if constexpr (SRC_F32) h = S.h32[i][j];
;             else { const v2u hw = S.hb[i][j]; h.x = bf_lo(hw.x); h.y = bf_hi(hw.x); h.z = bf_lo(hw.y); h.w = bf_hi(hw.y); }
;             const v2u fw = S.fw[i][j];
;             f32x4 v; v.x = h.x + bf_lo(fw.x) * rs * g[j].x; v.y = h.y + bf_hi(fw.x) * rs * g[j].y; v.z = h.z + bf_lo(fw.y) * rs * g[j].z; v.w = h.w + bf_hi(fw.y) * rs * g[j].w;
;             if (FINAL) __builtin_nontemporal_store(v, (f32x4*)(out32 + (size_t)(rb + i) * D) + lane + 64 * j);
	v_lshlrev_b32_e32 v248, 16, v178
	v_and_b32_e32 v249, 0xffff0000, v178
	v_pk_mul_f32 v[28:29], v[28:29], v[244:245] op_sel_hi:[1,0]
	v_pk_fma_f32 v[28:29], v[28:29], v[228:229], v[248:249]
	v_lshlrev_b32_e32 v250, 16, v179
	v_and_b32_e32 v251, 0xffff0000, v179
	v_pk_mul_f32 v[30:31], v[30:31], v[244:245] op_sel_hi:[1,0]
	v_pk_fma_f32 v[30:31], v[30:31], v[230:231], v[250:251]
	v_lshlrev_b32_e32 v252, 16, v180
	v_and_b32_e32 v253, 0xffff0000, v180
	v_pk_mul_f32 v[24:25], v[24:25], v[244:245] op_sel_hi:[1,0]
	v_pk_fma_f32 v[24:25], v[24:25], v[232:233], v[252:253]
	v_lshlrev_b32_e32 v248, 16, v181
	v_and_b32_e32 v249, 0xffff0000, v181
	v_pk_mul_f32 v[26:27], v[26:27], v[244:245] op_sel_hi:[1,0]
	v_pk_fma_f32 v[26:27], v[26:27], v[234:235], v[248:249]
	v_lshlrev_b32_e32 v250, 16, v182
	v_and_b32_e32 v251, 0xffff0000, v182
	v_pk_mul_f32 v[20:21], v[20:21], v[244:245] op_sel_hi:[1,0]
	v_pk_fma_f32 v[20:21], v[20:21], v[236:237], v[250:251]
	v_lshlrev_b32_e32 v252, 16, v183
	v_and_b32_e32 v253, 0xffff0000, v183
	v_pk_mul_f32 v[22:23], v[22:23], v[244:245] op_sel_hi:[1,0]
	v_pk_fma_f32 v[22:23], v[22:23], v[238:239], v[252:253]
	v_lshlrev_b32_e32 v248, 16, v184
	v_and_b32_e32 v249, 0xffff0000, v184
	v_pk_mul_f32 v[16:17], v[16:17], v[244:245] op_sel_hi:[1,0]
	v_pk_fma_f32 v[16:17], v[16:17], v[240:241], v[248:249]
	v_lshlrev_b32_e32 v250, 16, v185
	v_and_b32_e32 v251, 0xffff0000, v185
	v_pk_mul_f32 v[18:19], v[18:19], v[244:245] op_sel_hi:[1,0]
	v_pk_fma_f32 v[18:19], v[18:19], v[242:243], v[250:251]
	v_add_u32_e32 v161, 0x50000, v152
	v_lshlrev_b32_e32 v161, 1, v161
	global_store_dwordx4 v161, v[28:31], s[64:65] nt
	global_store_dwordx4 v161, v[24:27], s[64:65] offset:16 nt
	global_store_dwordx4 v161, v[20:23], s[64:65] offset:512 nt
	global_store_dwordx4 v161, v[16:19], s[64:65] offset:528 nt
	s_waitcnt vmcnt(20)
	v_lshlrev_b32_e32 v248, 16, v186
	v_and_b32_e32 v249, 0xffff0000, v186
	v_pk_mul_f32 v[12:13], v[12:13], v[246:247] op_sel_hi:[1,0]
	v_pk_fma_f32 v[12:13], v[12:13], v[228:229], v[248:249]
	v_lshlrev_b32_e32 v250, 16, v187
	v_and_b32_e32 v251, 0xffff0000, v187
	v_pk_mul_f32 v[14:15], v[14:15], v[246:247] op_sel_hi:[1,0]
	v_pk_fma_f32 v[14:15], v[14:15], v[230:231], v[250:251]
	v_lshlrev_b32_e32 v252, 16, v188
	v_and_b32_e32 v253, 0xffff0000, v188
	v_pk_mul_f32 v[8:9], v[8:9], v[246:247] op_sel_hi:[1,0]
	v_pk_fma_f32 v[8:9], v[8:9], v[232:233], v[252:253]
	v_lshlrev_b32_e32 v248, 16, v189
	v_and_b32_e32 v249, 0xffff0000, v189
	v_pk_mul_f32 v[10:11], v[10:11], v[246:247] op_sel_hi:[1,0]
	v_pk_fma_f32 v[10:11], v[10:11], v[234:235], v[248:249]
	v_lshlrev_b32_e32 v250, 16, v190
	v_and_b32_e32 v251, 0xffff0000, v190
	v_pk_mul_f32 v[4:5], v[4:5], v[246:247] op_sel_hi:[1,0]
	v_pk_fma_f32 v[4:5], v[4:5], v[236:237], v[250:251]
	v_lshlrev_b32_e32 v252, 16, v191
	v_and_b32_e32 v253, 0xffff0000, v191
	v_pk_mul_f32 v[6:7], v[6:7], v[246:247] op_sel_hi:[1,0]
	v_pk_fma_f32 v[6:7], v[6:7], v[238:239], v[252:253]
	v_lshlrev_b32_e32 v248, 16, v192
	v_and_b32_e32 v249, 0xffff0000, v192
	v_pk_mul_f32 v[0:1], v[0:1], v[246:247] op_sel_hi:[1,0]
	v_pk_fma_f32 v[0:1], v[0:1], v[240:241], v[248:249]
	v_lshlrev_b32_e32 v250, 16, v193
	v_and_b32_e32 v251, 0xffff0000, v193
	v_pk_mul_f32 v[2:3], v[2:3], v[246:247] op_sel_hi:[1,0]
	v_pk_fma_f32 v[2:3], v[2:3], v[242:243], v[250:251]
	v_add_u32_e32 v161, 0x58000, v152
	v_lshlrev_b32_e32 v161, 1, v161
	global_store_dwordx4 v161, v[12:15], s[64:65] nt
	global_store_dwordx4 v161, v[8:11], s[64:65] offset:16 nt
	global_store_dwordx4 v161, v[4:7], s[64:65] offset:512 nt
	global_store_dwordx4 v161, v[0:3], s[64:65] offset:528 nt
	s_and_b64 vcc, exec, s[4:5]
	s_mov_b64 s[4:5], -1
	s_cbranch_vccnz .LBB0_1376
	s_andn2_b64 vcc, exec, s[22:23]
	s_cbranch_vccnz .LBB0_1375
	s_barrier
	s_branch .LBB0_1375

; #define SEAM(k) do { if (IN(k) && IN((k) + 1)) { xcd_barrier(xbar); } } while (0)
; __global__ void __launch_bounds__(NWAVES * 64, 2) mk_fwd(Args a) {
;     ...
;     SEAM(13);
;     if (IN(14)) ew_phase<false, true>(nullptr, HB, nullptr, a.out, FB, PART, a.in[I_PLEPOST], 1.0f, nullptr, gw, NGW, lane);
.LBB0_1396:
	s_branch .LBB0_1474
.LBB0_1446:
.LBB0_1474:
	s_endpgm
